# grid barrier: all waiters poll the cross-XCD arrival counter against (round+1)*nx; the last leader no longer bumps a release generation
# speedup vs baseline: 1.0098x; 1.0062x over previous
.LBB0_683:
	s_or_b64 exec, exec, s[0:1]
	v_cvt_f32_u32_e32 v4, v2
	s_waitcnt vmcnt(0)
	v_readfirstlane_b32 s0, v3
	v_sub_u32_e32 v3, 0, v2
	v_rcp_iflag_f32_e32 v4, v4
	v_add_u32_e32 v5, s0, v1
	v_mul_f32_e32 v4, 0x4f7ffffe, v4
	v_cvt_u32_f32_e32 v4, v4
	v_mul_lo_u32 v1, v3, v4
	v_mul_hi_u32 v1, v4, v1
	v_add_u32_e32 v1, v4, v1
	v_mul_hi_u32 v1, v5, v1
	v_mul_lo_u32 v3, v1, v2
	v_sub_u32_e32 v3, v5, v3
	v_add_u32_e32 v4, 1, v1
	v_cmp_ge_u32_e32 vcc, v3, v2
	s_nop 1
	v_cndmask_b32_e32 v1, v1, v4, vcc
	v_sub_u32_e32 v4, v3, v2
	v_cndmask_b32_e32 v3, v3, v4, vcc
	v_add_u32_e32 v4, 1, v1
	v_cmp_ge_u32_e32 vcc, v3, v2
	v_add_u32_e32 v3, 1, v5
	s_nop 0
	v_cndmask_b32_e32 v1, v1, v4, vcc
	v_mul_lo_u32 v4, v2, v1
	v_add_u32_e32 v2, v4, v2
	v_cmp_ne_u32_e32 vcc, v3, v2
	s_and_saveexec_b64 s[0:1], vcc
	s_xor_b64 s[0:1], exec, s[0:1]
	s_cbranch_execz .LBB0_697
	v_readlane_b32 s4, v254, 11
	v_readlane_b32 s5, v254, 12
	s_waitcnt lgkmcnt(0)
	v_mad_u32_u24 v1, v1, v0, v0
	s_nop 3
	global_load_dword v0, v113, s[4:5] sc1
	s_waitcnt vmcnt(0)
	v_cmp_lt_u32_e32 vcc, v0, v1
	s_and_saveexec_b64 s[4:5], vcc
	s_cbranch_execz .LBB0_696
	s_mov_b32 s18, 1
	s_mov_b64 s[6:7], 0
	s_branch .LBB0_687

.LBB0_689:
	v_readlane_b32 s10, v254, 11
	v_readlane_b32 s11, v254, 12
	s_add_i32 s18, s18, 1
	s_mov_b64 s[12:13], -1
	s_nop 2
	global_load_dword v0, v113, s[10:11] sc1
	s_waitcnt vmcnt(0)
	v_cmp_ge_u32_e32 vcc, v0, v1
	s_orn2_b64 s[10:11], vcc, exec
	s_branch .LBB0_686

.LBB0_700:
	s_or_b64 exec, exec, s[4:5]
	s_waitcnt vmcnt(0)
	v_readfirstlane_b32 s0, v2
	v_cvt_f32_u32_e32 v2, v0
	v_sub_u32_e32 v3, 0, v0
	v_add_u32_e32 v1, s0, v1
	v_readlane_b32 s0, v254, 13
	v_rcp_iflag_f32_e32 v2, v2
	v_readlane_b32 s1, v254, 14
	s_mov_b64 s[4:5], 0
	v_mul_f32_e32 v2, 0x4f7ffffe, v2
	v_cvt_u32_f32_e32 v2, v2
	v_mul_lo_u32 v3, v3, v2
	v_mul_hi_u32 v3, v2, v3
	v_add_u32_e32 v2, v2, v3
	v_mul_hi_u32 v2, v1, v2
	v_mul_lo_u32 v3, v2, v0
	v_sub_u32_e32 v3, v1, v3
	v_cmp_ge_u32_e32 vcc, v3, v0
	v_add_u32_e32 v4, 1, v2
	v_add_u32_e32 v1, 1, v1
	v_cndmask_b32_e32 v2, v2, v4, vcc
	v_sub_u32_e32 v4, v3, v0
	v_cndmask_b32_e32 v3, v3, v4, vcc
	v_cmp_ge_u32_e32 vcc, v3, v0
	v_add_u32_e32 v3, 1, v2
	s_nop 0
	v_cndmask_b32_e32 v2, v2, v3, vcc
	v_mul_lo_u32 v3, v0, v2
	v_add_u32_e32 v0, v3, v0
	v_cmp_ne_u32_e32 vcc, v1, v0
	v_mov_b32_e32 v3, v0
	v_mov_b64_e32 v[0:1], s[0:1]
	s_and_saveexec_b64 s[0:1], vcc
	s_cbranch_execz .LBB0_712
	v_readlane_b32 s4, v254, 11
	v_readlane_b32 s5, v254, 12
	s_mov_b64 s[6:7], 0
	s_nop 3
	global_load_dword v0, v113, s[4:5] sc1
	s_waitcnt vmcnt(0)
	v_cmp_lt_u32_e32 vcc, v0, v3
	s_and_saveexec_b64 s[4:5], vcc
	s_cbranch_execz .LBB0_711
	s_mov_b32 s18, 1
	s_branch .LBB0_704

.LBB0_706:
	v_readlane_b32 s10, v254, 11
	v_readlane_b32 s11, v254, 12
	s_add_i32 s18, s18, 1
	s_mov_b64 s[12:13], -1
	s_nop 2
	global_load_dword v0, v113, s[10:11] sc1
	s_waitcnt vmcnt(0)
	v_cmp_ge_u32_e32 vcc, v0, v3
	s_orn2_b64 s[10:11], vcc, exec
	s_branch .LBB0_703
